# nt hint on the per-pass y partial stores of the peer_ffn sweep (protects the L2-resident expert slice)
# baseline (speedup 1.0000x reference)
; DI void phase_peer_ffn(const Params& p) {
;     ...
;   for (int tok = gw; tok < T_; tok += nw) {
;     float yacc[16];
; #pragma unroll
;     for (int i = 0; i < 16; ++i) yacc[i] = 0.f;
;     const int e_lo = eidx[(size_t)tok * 128 + lane];
;     const int e_hi = eidx[(size_t)tok * 128 + 64 + lane];
;     const float c_lo = coefw[(size_t)tok * 128 + lane];
;     const float c_hi = coefw[(size_t)tok * 128 + 64 + lane];
; #pragma unroll 1
;     for (int eb = 0; eb < 8; ++eb) {
;       const int ev = (eb < 4) ? e_lo : e_hi;
;       const float cv = (eb < 4) ? c_lo : c_hi;
;       const int lbase = (eb & 3) * 16;
;       u32x4 ur[16];
; #pragma unroll
;       for (int k = 0; k < 16; ++k) {
;         const int er = __builtin_amdgcn_readlane(ev, lbase + k);
;         ur[k] = *reinterpret_cast<const u32x4*>(exu + (size_t)er * 1024 + lane * 16);
;       }
; #pragma unroll
;       for (int k = 0; k < 16; ++k) {
;         const float ck = __int_as_float(__builtin_amdgcn_readlane(__float_as_int(cv), lbase + k));
; #pragma unroll
;         for (int w = 0; w < 4; ++w) {
;           f2_t lo = __builtin_amdgcn_cvt_pk_f32_fp8((int)ur[k][w], false);
;           f2_t hi = __builtin_amdgcn_cvt_pk_f32_fp8((int)ur[k][w], true);
;           yacc[4 * w] = fmaf(ck, lo[0], yacc[4 * w]);
;           yacc[4 * w + 1] = fmaf(ck, lo[1], yacc[4 * w + 1]);
;           yacc[4 * w + 2] = fmaf(ck, hi[0], yacc[4 * w + 2]);
;           yacc[4 * w + 3] = fmaf(ck, hi[1], yacc[4 * w + 3]);
;         }
.LBB0_1085:
	s_or_b64 exec, exec, s[4:5]
	s_waitcnt lgkmcnt(0)
	s_barrier
	s_and_saveexec_b64 s[4:5], s[2:3]
	s_cbranch_execz .LBB0_1090
	s_mov_b32 s2, s96
	s_mov_b32 s3, s97
	s_add_u32 s6, s96, 0x5000000
	s_addc_u32 s7, s97, 0
	s_add_u32 s8, s96, 0x2000000
	s_addc_u32 s9, s97, 0
	v_mbcnt_lo_u32_b32 v0, -1, 0
	v_mbcnt_hi_u32_b32 v0, -1, v0
	v_lshrrev_b32_e32 v1, 3, v0
	v_and_b32_e32 v2, 7, v0
	v_lshlrev_b32_e32 v2, 4, v2
	v_lshl_add_u32 v3, v1, 9, v2
	v_lshlrev_b32_e32 v1, 2, v1
	v_lshlrev_b32_e32 v4, 3, v0
	v_and_b32_e32 v5, 7, v64
	v_lshlrev_b32_e32 v5, 12, v5
	v_add_u32_e32 v3, v5, v3
	v_add_u32_e32 v4, v5, v4
	v_and_b32_e32 v5, 14, v0
	v_lshlrev_b32_e32 v5, 5, v5
	v_lshrrev_b32_e32 v6, 4, v0
	v_lshl_add_u32 v5, v6, 4, v5
	v_and_b32_e32 v6, 1, v0
	v_lshl_add_u32 v5, v6, 3, v5
	v_lshlrev_b32_e32 v148, 3, v0
	v_and_b32_e32 v149, 7, v64
	v_lshlrev_b32_e32 v149, 10, v149
	v_add_u32_e32 v149, 0x8000, v149
	v_lshl_add_u32 v150, v1, 4, v149
	v_add_u32_e32 v149, v148, v149
	v_lshl_add_u32 v9, v64, 9, v148
	global_load_dwordx2 v[152:153], v9, s[2:3]
	global_load_dwordx2 v[154:155], v9, s[8:9]
	s_waitcnt vmcnt(1)
	ds_write_b64 v149, v[152:153]
	ds_read_b128 v[100:103], v150 offset:0
	ds_read_b128 v[104:107], v150 offset:16
	ds_read_b128 v[108:111], v150 offset:32
	ds_read_b128 v[112:115], v150 offset:48
	v_add_u32_e32 v6, 0x800, v64
	v_lshl_add_u32 v9, v6, 9, v148
	global_load_dwordx2 v[152:153], v9, s[2:3]
	s_waitcnt lgkmcnt(0)
	v_lshl_add_u32 v11, v100, 10, v2
	global_load_dwordx4 v[180:183], v11, s[6:7]
	v_lshl_add_u32 v11, v101, 10, v2
	global_load_dwordx4 v[184:187], v11, s[6:7]
	v_lshl_add_u32 v11, v102, 10, v2
	global_load_dwordx4 v[188:191], v11, s[6:7]
	v_lshl_add_u32 v11, v103, 10, v2
	global_load_dwordx4 v[192:195], v11, s[6:7]
	v_lshl_add_u32 v11, v104, 10, v2
	global_load_dwordx4 v[196:199], v11, s[6:7]
	v_lshl_add_u32 v11, v105, 10, v2
	global_load_dwordx4 v[200:203], v11, s[6:7]
	v_lshl_add_u32 v11, v106, 10, v2
	global_load_dwordx4 v[204:207], v11, s[6:7]
	v_lshl_add_u32 v11, v107, 10, v2
	global_load_dwordx4 v[208:211], v11, s[6:7]
	v_lshl_add_u32 v11, v108, 10, v2
	global_load_dwordx4 v[212:215], v11, s[6:7]
	v_lshl_add_u32 v11, v109, 10, v2
	global_load_dwordx4 v[216:219], v11, s[6:7]
	v_lshl_add_u32 v11, v110, 10, v2
	global_load_dwordx4 v[220:223], v11, s[6:7]
	v_lshl_add_u32 v11, v111, 10, v2
	global_load_dwordx4 v[224:227], v11, s[6:7]
	v_lshl_add_u32 v11, v112, 10, v2
	global_load_dwordx4 v[228:231], v11, s[6:7]
	v_lshl_add_u32 v11, v113, 10, v2
	global_load_dwordx4 v[232:235], v11, s[6:7]
	v_lshl_add_u32 v11, v114, 10, v2
	global_load_dwordx4 v[236:239], v11, s[6:7]
	v_lshl_add_u32 v11, v115, 10, v2
	global_load_dwordx4 v[240:243], v11, s[6:7]
	v_lshl_add_u32 v12, v64, 12, v5
	global_store_dwordx2 v12, v[82:83], s[58:59] nt
	s_mov_b32 s18, 0
.Lpf_loop:
	s_add_i32 s20, s18, 1
	s_min_i32 s20, s20, 0x7f
	s_lshr_b32 s21, s20, 4
	s_and_b32 s22, s20, 15
	s_add_i32 s23, s18, 2
	s_min_i32 s23, s23, 0x7f
	s_and_b32 s24, s23, 15
	s_and_b32 s26, s18, 15
	s_lshr_b32 s27, s18, 4
	s_lshl_b32 s22, s22, 11
	s_lshl_b32 s24, s24, 11
	s_lshl_b32 s28, s21, 7
	s_lshl_b32 s26, s26, 11
	s_lshl_b32 s27, s27, 9
	v_add_u32_e32 v6, s22, v64
	v_add_u32_e32 v7, s24, v64
	v_add_u32_e32 v8, s28, v2
	v_lshl_add_u32 v10, v6, 9, v148
	v_lshl_add_u32 v9, v7, 9, v148
	v_add_u32_e32 v12, s26, v64
	v_lshl_add_u32 v12, v12, 12, v5
	v_add_u32_e32 v12, s27, v12
	s_waitcnt vmcnt(17)
	ds_write_b64 v149, v[152:153]
	ds_write_b64 v149, v[154:155] offset:512
	ds_read_b128 v[100:103], v150 offset:0
	ds_read_b128 v[104:107], v150 offset:16
	ds_read_b128 v[108:111], v150 offset:32
	ds_read_b128 v[112:115], v150 offset:48
	ds_read_b128 v[132:135], v150 offset:512
	ds_read_b128 v[136:139], v150 offset:528
	ds_read_b128 v[140:143], v150 offset:544
	ds_read_b128 v[144:147], v150 offset:560
	global_load_dwordx2 v[152:153], v9, s[2:3]
	global_load_dwordx2 v[154:155], v10, s[8:9]
	s_waitcnt lgkmcnt(0)
	s_waitcnt vmcnt(17)
	v_cvt_pk_f32_fp8_e32 v[44:45], v180
	v_cvt_pk_f32_fp8_sdwa v[46:47], v180 src0_sel:WORD_1
	v_cvt_pk_f32_fp8_e32 v[48:49], v181
	v_cvt_pk_f32_fp8_sdwa v[50:51], v181 src0_sel:WORD_1
	v_cvt_pk_f32_fp8_e32 v[52:53], v182
	v_cvt_pk_f32_fp8_sdwa v[54:55], v182 src0_sel:WORD_1
	v_cvt_pk_f32_fp8_e32 v[56:57], v183
	v_cvt_pk_f32_fp8_sdwa v[58:59], v183 src0_sel:WORD_1
	v_cvt_pk_f32_fp8_e32 v[66:67], v184
	v_cvt_pk_f32_fp8_sdwa v[68:69], v184 src0_sel:WORD_1
	v_cvt_pk_f32_fp8_e32 v[70:71], v185
	v_cvt_pk_f32_fp8_sdwa v[72:73], v185 src0_sel:WORD_1
	v_cvt_pk_f32_fp8_e32 v[74:75], v186
	v_cvt_pk_f32_fp8_sdwa v[76:77], v186 src0_sel:WORD_1
	v_cvt_pk_f32_fp8_e32 v[78:79], v187
	v_cvt_pk_f32_fp8_sdwa v[80:81], v187 src0_sel:WORD_1
	v_lshl_add_u32 v11, v100, 10, v8
	v_lshl_add_u32 v65, v101, 10, v8
	global_load_dwordx4 v[180:183], v11, s[6:7]
	global_load_dwordx4 v[184:187], v65, s[6:7]
	v_pk_mul_f32 v[20:21], v[44:45], v[132:133] op_sel_hi:[1,0]
	v_pk_mul_f32 v[22:23], v[46:47], v[132:133] op_sel_hi:[1,0]
	v_pk_mul_f32 v[24:25], v[48:49], v[132:133] op_sel_hi:[1,0]
	v_pk_mul_f32 v[26:27], v[50:51], v[132:133] op_sel_hi:[1,0]
	v_pk_mul_f32 v[28:29], v[52:53], v[132:133] op_sel_hi:[1,0]
	v_pk_mul_f32 v[30:31], v[54:55], v[132:133] op_sel_hi:[1,0]
	v_pk_mul_f32 v[32:33], v[56:57], v[132:133] op_sel_hi:[1,0]
	v_pk_mul_f32 v[34:35], v[58:59], v[132:133] op_sel_hi:[1,0]
	v_pk_fma_f32 v[20:21], v[66:67], v[132:133], v[20:21] op_sel:[0,1,0]
	v_pk_fma_f32 v[22:23], v[68:69], v[132:133], v[22:23] op_sel:[0,1,0]
	v_pk_fma_f32 v[24:25], v[70:71], v[132:133], v[24:25] op_sel:[0,1,0]
	v_pk_fma_f32 v[26:27], v[72:73], v[132:133], v[26:27] op_sel:[0,1,0]
	v_pk_fma_f32 v[28:29], v[74:75], v[132:133], v[28:29] op_sel:[0,1,0]
	v_pk_fma_f32 v[30:31], v[76:77], v[132:133], v[30:31] op_sel:[0,1,0]
	v_pk_fma_f32 v[32:33], v[78:79], v[132:133], v[32:33] op_sel:[0,1,0]
	v_pk_fma_f32 v[34:35], v[80:81], v[132:133], v[34:35] op_sel:[0,1,0]
	s_waitcnt vmcnt(17)
; DI void phase_peer_ffn(const Params& p) {
;     ...
; #pragma unroll
;       for (int k = 0; k < 16; ++k) {
;         const float ck = __int_as_float(__builtin_amdgcn_readlane(__float_as_int(cv), lbase + k));
; #pragma unroll
;         for (int w = 0; w < 4; ++w) {
;           f2_t lo = __builtin_amdgcn_cvt_pk_f32_fp8((int)ur[k][w], false);
;           f2_t hi = __builtin_amdgcn_cvt_pk_f32_fp8((int)ur[k][w], true);
;           yacc[4 * w] = fmaf(ck, lo[0], yacc[4 * w]);
;           yacc[4 * w + 1] = fmaf(ck, lo[1], yacc[4 * w + 1]);
;           yacc[4 * w + 2] = fmaf(ck, hi[0], yacc[4 * w + 2]);
;           yacc[4 * w + 3] = fmaf(ck, hi[1], yacc[4 * w + 3]);
;         }
	v_cvt_pk_f32_fp8_e32 v[44:45], v188
	v_cvt_pk_f32_fp8_sdwa v[46:47], v188 src0_sel:WORD_1
	v_cvt_pk_f32_fp8_e32 v[48:49], v189
	v_cvt_pk_f32_fp8_sdwa v[50:51], v189 src0_sel:WORD_1
	v_cvt_pk_f32_fp8_e32 v[52:53], v190
	v_cvt_pk_f32_fp8_sdwa v[54:55], v190 src0_sel:WORD_1
	v_cvt_pk_f32_fp8_e32 v[56:57], v191
	v_cvt_pk_f32_fp8_sdwa v[58:59], v191 src0_sel:WORD_1
	v_cvt_pk_f32_fp8_e32 v[66:67], v192
	v_cvt_pk_f32_fp8_sdwa v[68:69], v192 src0_sel:WORD_1
	v_cvt_pk_f32_fp8_e32 v[70:71], v193
	v_cvt_pk_f32_fp8_sdwa v[72:73], v193 src0_sel:WORD_1
	v_cvt_pk_f32_fp8_e32 v[74:75], v194
	v_cvt_pk_f32_fp8_sdwa v[76:77], v194 src0_sel:WORD_1
	v_cvt_pk_f32_fp8_e32 v[78:79], v195
	v_cvt_pk_f32_fp8_sdwa v[80:81], v195 src0_sel:WORD_1
	v_lshl_add_u32 v11, v102, 10, v8
	v_lshl_add_u32 v65, v103, 10, v8
	global_load_dwordx4 v[188:191], v11, s[6:7]
	global_load_dwordx4 v[192:195], v65, s[6:7]
	v_pk_fma_f32 v[20:21], v[44:45], v[134:135], v[20:21] op_sel_hi:[1,0,1]
	v_pk_fma_f32 v[22:23], v[46:47], v[134:135], v[22:23] op_sel_hi:[1,0,1]
	v_pk_fma_f32 v[24:25], v[48:49], v[134:135], v[24:25] op_sel_hi:[1,0,1]
	v_pk_fma_f32 v[26:27], v[50:51], v[134:135], v[26:27] op_sel_hi:[1,0,1]
	v_pk_fma_f32 v[28:29], v[52:53], v[134:135], v[28:29] op_sel_hi:[1,0,1]
	v_pk_fma_f32 v[30:31], v[54:55], v[134:135], v[30:31] op_sel_hi:[1,0,1]
	v_pk_fma_f32 v[32:33], v[56:57], v[134:135], v[32:33] op_sel_hi:[1,0,1]
	v_pk_fma_f32 v[34:35], v[58:59], v[134:135], v[34:35] op_sel_hi:[1,0,1]
	v_pk_fma_f32 v[20:21], v[66:67], v[134:135], v[20:21] op_sel:[0,1,0]
	v_pk_fma_f32 v[22:23], v[68:69], v[134:135], v[22:23] op_sel:[0,1,0]
	v_pk_fma_f32 v[24:25], v[70:71], v[134:135], v[24:25] op_sel:[0,1,0]
	v_pk_fma_f32 v[26:27], v[72:73], v[134:135], v[26:27] op_sel:[0,1,0]
	v_pk_fma_f32 v[28:29], v[74:75], v[134:135], v[28:29] op_sel:[0,1,0]
	v_pk_fma_f32 v[30:31], v[76:77], v[134:135], v[30:31] op_sel:[0,1,0]
	v_pk_fma_f32 v[32:33], v[78:79], v[134:135], v[32:33] op_sel:[0,1,0]
	v_pk_fma_f32 v[34:35], v[80:81], v[134:135], v[34:35] op_sel:[0,1,0]
	s_waitcnt vmcnt(17)
	v_cvt_pk_f32_fp8_e32 v[44:45], v196
	v_cvt_pk_f32_fp8_sdwa v[46:47], v196 src0_sel:WORD_1
	v_cvt_pk_f32_fp8_e32 v[48:49], v197
	v_cvt_pk_f32_fp8_sdwa v[50:51], v197 src0_sel:WORD_1
	v_cvt_pk_f32_fp8_e32 v[52:53], v198
	v_cvt_pk_f32_fp8_sdwa v[54:55], v198 src0_sel:WORD_1
	v_cvt_pk_f32_fp8_e32 v[56:57], v199
	v_cvt_pk_f32_fp8_sdwa v[58:59], v199 src0_sel:WORD_1
	v_cvt_pk_f32_fp8_e32 v[66:67], v200
	v_cvt_pk_f32_fp8_sdwa v[68:69], v200 src0_sel:WORD_1
	v_cvt_pk_f32_fp8_e32 v[70:71], v201
	v_cvt_pk_f32_fp8_sdwa v[72:73], v201 src0_sel:WORD_1
	v_cvt_pk_f32_fp8_e32 v[74:75], v202
	v_cvt_pk_f32_fp8_sdwa v[76:77], v202 src0_sel:WORD_1
	v_cvt_pk_f32_fp8_e32 v[78:79], v203
	v_cvt_pk_f32_fp8_sdwa v[80:81], v203 src0_sel:WORD_1
	v_lshl_add_u32 v11, v104, 10, v8
	v_lshl_add_u32 v65, v105, 10, v8
	global_load_dwordx4 v[196:199], v11, s[6:7]
	global_load_dwordx4 v[200:203], v65, s[6:7]
	v_pk_fma_f32 v[20:21], v[44:45], v[136:137], v[20:21] op_sel_hi:[1,0,1]
	v_pk_fma_f32 v[22:23], v[46:47], v[136:137], v[22:23] op_sel_hi:[1,0,1]
	v_pk_fma_f32 v[24:25], v[48:49], v[136:137], v[24:25] op_sel_hi:[1,0,1]
	v_pk_fma_f32 v[26:27], v[50:51], v[136:137], v[26:27] op_sel_hi:[1,0,1]
	v_pk_fma_f32 v[28:29], v[52:53], v[136:137], v[28:29] op_sel_hi:[1,0,1]
	v_pk_fma_f32 v[30:31], v[54:55], v[136:137], v[30:31] op_sel_hi:[1,0,1]
	v_pk_fma_f32 v[32:33], v[56:57], v[136:137], v[32:33] op_sel_hi:[1,0,1]
	v_pk_fma_f32 v[34:35], v[58:59], v[136:137], v[34:35] op_sel_hi:[1,0,1]
	v_pk_fma_f32 v[20:21], v[66:67], v[136:137], v[20:21] op_sel:[0,1,0]
	v_pk_fma_f32 v[22:23], v[68:69], v[136:137], v[22:23] op_sel:[0,1,0]
	v_pk_fma_f32 v[24:25], v[70:71], v[136:137], v[24:25] op_sel:[0,1,0]
	v_pk_fma_f32 v[26:27], v[72:73], v[136:137], v[26:27] op_sel:[0,1,0]
	v_pk_fma_f32 v[28:29], v[74:75], v[136:137], v[28:29] op_sel:[0,1,0]
	v_pk_fma_f32 v[30:31], v[76:77], v[136:137], v[30:31] op_sel:[0,1,0]
	v_pk_fma_f32 v[32:33], v[78:79], v[136:137], v[32:33] op_sel:[0,1,0]
	v_pk_fma_f32 v[34:35], v[80:81], v[136:137], v[34:35] op_sel:[0,1,0]
	s_waitcnt vmcnt(17)
	v_cvt_pk_f32_fp8_e32 v[44:45], v204
	v_cvt_pk_f32_fp8_sdwa v[46:47], v204 src0_sel:WORD_1
	v_cvt_pk_f32_fp8_e32 v[48:49], v205
	v_cvt_pk_f32_fp8_sdwa v[50:51], v205 src0_sel:WORD_1
	v_cvt_pk_f32_fp8_e32 v[52:53], v206
	v_cvt_pk_f32_fp8_sdwa v[54:55], v206 src0_sel:WORD_1
	v_cvt_pk_f32_fp8_e32 v[56:57], v207
	v_cvt_pk_f32_fp8_sdwa v[58:59], v207 src0_sel:WORD_1
	v_cvt_pk_f32_fp8_e32 v[66:67], v208
	v_cvt_pk_f32_fp8_sdwa v[68:69], v208 src0_sel:WORD_1
	v_cvt_pk_f32_fp8_e32 v[70:71], v209
	v_cvt_pk_f32_fp8_sdwa v[72:73], v209 src0_sel:WORD_1
	v_cvt_pk_f32_fp8_e32 v[74:75], v210
	v_cvt_pk_f32_fp8_sdwa v[76:77], v210 src0_sel:WORD_1
	v_cvt_pk_f32_fp8_e32 v[78:79], v211
	v_cvt_pk_f32_fp8_sdwa v[80:81], v211 src0_sel:WORD_1
	v_lshl_add_u32 v11, v106, 10, v8
	v_lshl_add_u32 v65, v107, 10, v8
	global_load_dwordx4 v[204:207], v11, s[6:7]
	global_load_dwordx4 v[208:211], v65, s[6:7]
	v_pk_fma_f32 v[20:21], v[44:45], v[138:139], v[20:21] op_sel_hi:[1,0,1]
	v_pk_fma_f32 v[22:23], v[46:47], v[138:139], v[22:23] op_sel_hi:[1,0,1]
	v_pk_fma_f32 v[24:25], v[48:49], v[138:139], v[24:25] op_sel_hi:[1,0,1]
	v_pk_fma_f32 v[26:27], v[50:51], v[138:139], v[26:27] op_sel_hi:[1,0,1]
	v_pk_fma_f32 v[28:29], v[52:53], v[138:139], v[28:29] op_sel_hi:[1,0,1]
	v_pk_fma_f32 v[30:31], v[54:55], v[138:139], v[30:31] op_sel_hi:[1,0,1]
	v_pk_fma_f32 v[32:33], v[56:57], v[138:139], v[32:33] op_sel_hi:[1,0,1]
	v_pk_fma_f32 v[34:35], v[58:59], v[138:139], v[34:35] op_sel_hi:[1,0,1]
	v_pk_fma_f32 v[20:21], v[66:67], v[138:139], v[20:21] op_sel:[0,1,0]
	v_pk_fma_f32 v[22:23], v[68:69], v[138:139], v[22:23] op_sel:[0,1,0]
	v_pk_fma_f32 v[24:25], v[70:71], v[138:139], v[24:25] op_sel:[0,1,0]
	v_pk_fma_f32 v[26:27], v[72:73], v[138:139], v[26:27] op_sel:[0,1,0]
	v_pk_fma_f32 v[28:29], v[74:75], v[138:139], v[28:29] op_sel:[0,1,0]
	v_pk_fma_f32 v[30:31], v[76:77], v[138:139], v[30:31] op_sel:[0,1,0]
	v_pk_fma_f32 v[32:33], v[78:79], v[138:139], v[32:33] op_sel:[0,1,0]
	v_pk_fma_f32 v[34:35], v[80:81], v[138:139], v[34:35] op_sel:[0,1,0]
	s_waitcnt vmcnt(17)
; DI void phase_peer_ffn(const Params& p) {
;     ...
; #pragma unroll
;       for (int k = 0; k < 16; ++k) {
;         const float ck = __int_as_float(__builtin_amdgcn_readlane(__float_as_int(cv), lbase + k));
; #pragma unroll
;         for (int w = 0; w < 4; ++w) {
;           f2_t lo = __builtin_amdgcn_cvt_pk_f32_fp8((int)ur[k][w], false);
;           f2_t hi = __builtin_amdgcn_cvt_pk_f32_fp8((int)ur[k][w], true);
;           yacc[4 * w] = fmaf(ck, lo[0], yacc[4 * w]);
;           yacc[4 * w + 1] = fmaf(ck, lo[1], yacc[4 * w + 1]);
;           yacc[4 * w + 2] = fmaf(ck, hi[0], yacc[4 * w + 2]);
;           yacc[4 * w + 3] = fmaf(ck, hi[1], yacc[4 * w + 3]);
;         }
	v_cvt_pk_f32_fp8_e32 v[44:45], v212
	v_cvt_pk_f32_fp8_sdwa v[46:47], v212 src0_sel:WORD_1
	v_cvt_pk_f32_fp8_e32 v[48:49], v213
	v_cvt_pk_f32_fp8_sdwa v[50:51], v213 src0_sel:WORD_1
	v_cvt_pk_f32_fp8_e32 v[52:53], v214
	v_cvt_pk_f32_fp8_sdwa v[54:55], v214 src0_sel:WORD_1
	v_cvt_pk_f32_fp8_e32 v[56:57], v215
	v_cvt_pk_f32_fp8_sdwa v[58:59], v215 src0_sel:WORD_1
	v_cvt_pk_f32_fp8_e32 v[66:67], v216
	v_cvt_pk_f32_fp8_sdwa v[68:69], v216 src0_sel:WORD_1
	v_cvt_pk_f32_fp8_e32 v[70:71], v217
	v_cvt_pk_f32_fp8_sdwa v[72:73], v217 src0_sel:WORD_1
	v_cvt_pk_f32_fp8_e32 v[74:75], v218
	v_cvt_pk_f32_fp8_sdwa v[76:77], v218 src0_sel:WORD_1
	v_cvt_pk_f32_fp8_e32 v[78:79], v219
	v_cvt_pk_f32_fp8_sdwa v[80:81], v219 src0_sel:WORD_1
	v_lshl_add_u32 v11, v108, 10, v8
	v_lshl_add_u32 v65, v109, 10, v8
	global_load_dwordx4 v[212:215], v11, s[6:7]
	global_load_dwordx4 v[216:219], v65, s[6:7]
	v_pk_fma_f32 v[20:21], v[44:45], v[140:141], v[20:21] op_sel_hi:[1,0,1]
	v_pk_fma_f32 v[22:23], v[46:47], v[140:141], v[22:23] op_sel_hi:[1,0,1]
	v_pk_fma_f32 v[24:25], v[48:49], v[140:141], v[24:25] op_sel_hi:[1,0,1]
	v_pk_fma_f32 v[26:27], v[50:51], v[140:141], v[26:27] op_sel_hi:[1,0,1]
	v_pk_fma_f32 v[28:29], v[52:53], v[140:141], v[28:29] op_sel_hi:[1,0,1]
	v_pk_fma_f32 v[30:31], v[54:55], v[140:141], v[30:31] op_sel_hi:[1,0,1]
	v_pk_fma_f32 v[32:33], v[56:57], v[140:141], v[32:33] op_sel_hi:[1,0,1]
	v_pk_fma_f32 v[34:35], v[58:59], v[140:141], v[34:35] op_sel_hi:[1,0,1]
	v_pk_fma_f32 v[20:21], v[66:67], v[140:141], v[20:21] op_sel:[0,1,0]
	v_pk_fma_f32 v[22:23], v[68:69], v[140:141], v[22:23] op_sel:[0,1,0]
	v_pk_fma_f32 v[24:25], v[70:71], v[140:141], v[24:25] op_sel:[0,1,0]
	v_pk_fma_f32 v[26:27], v[72:73], v[140:141], v[26:27] op_sel:[0,1,0]
	v_pk_fma_f32 v[28:29], v[74:75], v[140:141], v[28:29] op_sel:[0,1,0]
	v_pk_fma_f32 v[30:31], v[76:77], v[140:141], v[30:31] op_sel:[0,1,0]
	v_pk_fma_f32 v[32:33], v[78:79], v[140:141], v[32:33] op_sel:[0,1,0]
	v_pk_fma_f32 v[34:35], v[80:81], v[140:141], v[34:35] op_sel:[0,1,0]
	s_waitcnt vmcnt(17)
	v_cvt_pk_f32_fp8_e32 v[44:45], v220
	v_cvt_pk_f32_fp8_sdwa v[46:47], v220 src0_sel:WORD_1
	v_cvt_pk_f32_fp8_e32 v[48:49], v221
	v_cvt_pk_f32_fp8_sdwa v[50:51], v221 src0_sel:WORD_1
	v_cvt_pk_f32_fp8_e32 v[52:53], v222
	v_cvt_pk_f32_fp8_sdwa v[54:55], v222 src0_sel:WORD_1
	v_cvt_pk_f32_fp8_e32 v[56:57], v223
	v_cvt_pk_f32_fp8_sdwa v[58:59], v223 src0_sel:WORD_1
	v_cvt_pk_f32_fp8_e32 v[66:67], v224
	v_cvt_pk_f32_fp8_sdwa v[68:69], v224 src0_sel:WORD_1
	v_cvt_pk_f32_fp8_e32 v[70:71], v225
	v_cvt_pk_f32_fp8_sdwa v[72:73], v225 src0_sel:WORD_1
	v_cvt_pk_f32_fp8_e32 v[74:75], v226
	v_cvt_pk_f32_fp8_sdwa v[76:77], v226 src0_sel:WORD_1
	v_cvt_pk_f32_fp8_e32 v[78:79], v227
	v_cvt_pk_f32_fp8_sdwa v[80:81], v227 src0_sel:WORD_1
	v_lshl_add_u32 v11, v110, 10, v8
	v_lshl_add_u32 v65, v111, 10, v8
	global_load_dwordx4 v[220:223], v11, s[6:7]
	global_load_dwordx4 v[224:227], v65, s[6:7]
	v_pk_fma_f32 v[20:21], v[44:45], v[142:143], v[20:21] op_sel_hi:[1,0,1]
	v_pk_fma_f32 v[22:23], v[46:47], v[142:143], v[22:23] op_sel_hi:[1,0,1]
	v_pk_fma_f32 v[24:25], v[48:49], v[142:143], v[24:25] op_sel_hi:[1,0,1]
	v_pk_fma_f32 v[26:27], v[50:51], v[142:143], v[26:27] op_sel_hi:[1,0,1]
	v_pk_fma_f32 v[28:29], v[52:53], v[142:143], v[28:29] op_sel_hi:[1,0,1]
	v_pk_fma_f32 v[30:31], v[54:55], v[142:143], v[30:31] op_sel_hi:[1,0,1]
	v_pk_fma_f32 v[32:33], v[56:57], v[142:143], v[32:33] op_sel_hi:[1,0,1]
	v_pk_fma_f32 v[34:35], v[58:59], v[142:143], v[34:35] op_sel_hi:[1,0,1]
	v_pk_fma_f32 v[20:21], v[66:67], v[142:143], v[20:21] op_sel:[0,1,0]
	v_pk_fma_f32 v[22:23], v[68:69], v[142:143], v[22:23] op_sel:[0,1,0]
	v_pk_fma_f32 v[24:25], v[70:71], v[142:143], v[24:25] op_sel:[0,1,0]
	v_pk_fma_f32 v[26:27], v[72:73], v[142:143], v[26:27] op_sel:[0,1,0]
	v_pk_fma_f32 v[28:29], v[74:75], v[142:143], v[28:29] op_sel:[0,1,0]
	v_pk_fma_f32 v[30:31], v[76:77], v[142:143], v[30:31] op_sel:[0,1,0]
	v_pk_fma_f32 v[32:33], v[78:79], v[142:143], v[32:33] op_sel:[0,1,0]
	v_pk_fma_f32 v[34:35], v[80:81], v[142:143], v[34:35] op_sel:[0,1,0]
	s_waitcnt vmcnt(17)
	v_cvt_pk_f32_fp8_e32 v[44:45], v228
	v_cvt_pk_f32_fp8_sdwa v[46:47], v228 src0_sel:WORD_1
	v_cvt_pk_f32_fp8_e32 v[48:49], v229
	v_cvt_pk_f32_fp8_sdwa v[50:51], v229 src0_sel:WORD_1
	v_cvt_pk_f32_fp8_e32 v[52:53], v230
	v_cvt_pk_f32_fp8_sdwa v[54:55], v230 src0_sel:WORD_1
	v_cvt_pk_f32_fp8_e32 v[56:57], v231
	v_cvt_pk_f32_fp8_sdwa v[58:59], v231 src0_sel:WORD_1
	v_cvt_pk_f32_fp8_e32 v[66:67], v232
	v_cvt_pk_f32_fp8_sdwa v[68:69], v232 src0_sel:WORD_1
	v_cvt_pk_f32_fp8_e32 v[70:71], v233
	v_cvt_pk_f32_fp8_sdwa v[72:73], v233 src0_sel:WORD_1
	v_cvt_pk_f32_fp8_e32 v[74:75], v234
	v_cvt_pk_f32_fp8_sdwa v[76:77], v234 src0_sel:WORD_1
	v_cvt_pk_f32_fp8_e32 v[78:79], v235
	v_cvt_pk_f32_fp8_sdwa v[80:81], v235 src0_sel:WORD_1
	v_lshl_add_u32 v11, v112, 10, v8
	v_lshl_add_u32 v65, v113, 10, v8
	global_load_dwordx4 v[228:231], v11, s[6:7]
	global_load_dwordx4 v[232:235], v65, s[6:7]
	v_pk_fma_f32 v[20:21], v[44:45], v[144:145], v[20:21] op_sel_hi:[1,0,1]
	v_pk_fma_f32 v[22:23], v[46:47], v[144:145], v[22:23] op_sel_hi:[1,0,1]
	v_pk_fma_f32 v[24:25], v[48:49], v[144:145], v[24:25] op_sel_hi:[1,0,1]
	v_pk_fma_f32 v[26:27], v[50:51], v[144:145], v[26:27] op_sel_hi:[1,0,1]
	v_pk_fma_f32 v[28:29], v[52:53], v[144:145], v[28:29] op_sel_hi:[1,0,1]
	v_pk_fma_f32 v[30:31], v[54:55], v[144:145], v[30:31] op_sel_hi:[1,0,1]
	v_pk_fma_f32 v[32:33], v[56:57], v[144:145], v[32:33] op_sel_hi:[1,0,1]
	v_pk_fma_f32 v[34:35], v[58:59], v[144:145], v[34:35] op_sel_hi:[1,0,1]
	v_pk_fma_f32 v[20:21], v[66:67], v[144:145], v[20:21] op_sel:[0,1,0]
	v_pk_fma_f32 v[22:23], v[68:69], v[144:145], v[22:23] op_sel:[0,1,0]
	v_pk_fma_f32 v[24:25], v[70:71], v[144:145], v[24:25] op_sel:[0,1,0]
	v_pk_fma_f32 v[26:27], v[72:73], v[144:145], v[26:27] op_sel:[0,1,0]
	v_pk_fma_f32 v[28:29], v[74:75], v[144:145], v[28:29] op_sel:[0,1,0]
	v_pk_fma_f32 v[30:31], v[76:77], v[144:145], v[30:31] op_sel:[0,1,0]
	v_pk_fma_f32 v[32:33], v[78:79], v[144:145], v[32:33] op_sel:[0,1,0]
	v_pk_fma_f32 v[34:35], v[80:81], v[144:145], v[34:35] op_sel:[0,1,0]
	s_waitcnt vmcnt(17)
; DI void phase_peer_ffn(const Params& p) {
;     ...
; #pragma unroll
;       for (int k = 0; k < 16; ++k) {
;         const float ck = __int_as_float(__builtin_amdgcn_readlane(__float_as_int(cv), lbase + k));
; #pragma unroll
;         for (int w = 0; w < 4; ++w) {
;           f2_t lo = __builtin_amdgcn_cvt_pk_f32_fp8((int)ur[k][w], false);
;           f2_t hi = __builtin_amdgcn_cvt_pk_f32_fp8((int)ur[k][w], true);
;           yacc[4 * w] = fmaf(ck, lo[0], yacc[4 * w]);
;           yacc[4 * w + 1] = fmaf(ck, lo[1], yacc[4 * w + 1]);
;           yacc[4 * w + 2] = fmaf(ck, hi[0], yacc[4 * w + 2]);
;           yacc[4 * w + 3] = fmaf(ck, hi[1], yacc[4 * w + 3]);
;         }
;       }
;     }
	v_cvt_pk_f32_fp8_e32 v[44:45], v236
	v_cvt_pk_f32_fp8_sdwa v[46:47], v236 src0_sel:WORD_1
	v_cvt_pk_f32_fp8_e32 v[48:49], v237
	v_cvt_pk_f32_fp8_sdwa v[50:51], v237 src0_sel:WORD_1
	v_cvt_pk_f32_fp8_e32 v[52:53], v238
	v_cvt_pk_f32_fp8_sdwa v[54:55], v238 src0_sel:WORD_1
	v_cvt_pk_f32_fp8_e32 v[56:57], v239
	v_cvt_pk_f32_fp8_sdwa v[58:59], v239 src0_sel:WORD_1
	v_cvt_pk_f32_fp8_e32 v[66:67], v240
	v_cvt_pk_f32_fp8_sdwa v[68:69], v240 src0_sel:WORD_1
	v_cvt_pk_f32_fp8_e32 v[70:71], v241
	v_cvt_pk_f32_fp8_sdwa v[72:73], v241 src0_sel:WORD_1
	v_cvt_pk_f32_fp8_e32 v[74:75], v242
	v_cvt_pk_f32_fp8_sdwa v[76:77], v242 src0_sel:WORD_1
	v_cvt_pk_f32_fp8_e32 v[78:79], v243
	v_cvt_pk_f32_fp8_sdwa v[80:81], v243 src0_sel:WORD_1
	v_lshl_add_u32 v11, v114, 10, v8
	v_lshl_add_u32 v65, v115, 10, v8
	global_load_dwordx4 v[236:239], v11, s[6:7]
	global_load_dwordx4 v[240:243], v65, s[6:7]
	v_pk_fma_f32 v[20:21], v[44:45], v[146:147], v[20:21] op_sel_hi:[1,0,1]
	v_pk_fma_f32 v[22:23], v[46:47], v[146:147], v[22:23] op_sel_hi:[1,0,1]
	v_pk_fma_f32 v[24:25], v[48:49], v[146:147], v[24:25] op_sel_hi:[1,0,1]
	v_pk_fma_f32 v[26:27], v[50:51], v[146:147], v[26:27] op_sel_hi:[1,0,1]
	v_pk_fma_f32 v[28:29], v[52:53], v[146:147], v[28:29] op_sel_hi:[1,0,1]
	v_pk_fma_f32 v[30:31], v[54:55], v[146:147], v[30:31] op_sel_hi:[1,0,1]
	v_pk_fma_f32 v[32:33], v[56:57], v[146:147], v[32:33] op_sel_hi:[1,0,1]
	v_pk_fma_f32 v[34:35], v[58:59], v[146:147], v[34:35] op_sel_hi:[1,0,1]
	v_pk_fma_f32 v[20:21], v[66:67], v[146:147], v[20:21] op_sel:[0,1,0]
	v_pk_fma_f32 v[22:23], v[68:69], v[146:147], v[22:23] op_sel:[0,1,0]
	v_pk_fma_f32 v[24:25], v[70:71], v[146:147], v[24:25] op_sel:[0,1,0]
	v_pk_fma_f32 v[26:27], v[72:73], v[146:147], v[26:27] op_sel:[0,1,0]
	v_pk_fma_f32 v[28:29], v[74:75], v[146:147], v[28:29] op_sel:[0,1,0]
	v_pk_fma_f32 v[30:31], v[76:77], v[146:147], v[30:31] op_sel:[0,1,0]
	v_pk_fma_f32 v[32:33], v[78:79], v[146:147], v[32:33] op_sel:[0,1,0]
	v_pk_fma_f32 v[34:35], v[80:81], v[146:147], v[34:35] op_sel:[0,1,0]
	ds_write_b128 v3, v[20:23] offset:0
	ds_write_b128 v3, v[24:27] offset:128
	ds_write_b128 v3, v[28:31] offset:256
	ds_write_b128 v3, v[32:35] offset:384
	ds_read_b64 v[82:83], v4 offset:0
	ds_read_b64 v[84:85], v4 offset:512
	ds_read_b64 v[86:87], v4 offset:1024
	ds_read_b64 v[88:89], v4 offset:1536
	ds_read_b64 v[90:91], v4 offset:2048
	ds_read_b64 v[92:93], v4 offset:2560
	ds_read_b64 v[94:95], v4 offset:3072
	ds_read_b64 v[96:97], v4 offset:3584
	s_waitcnt lgkmcnt(0)
	v_pk_add_f32 v[82:83], v[82:83], v[84:85]
	v_pk_add_f32 v[86:87], v[86:87], v[88:89]
	v_pk_add_f32 v[90:91], v[90:91], v[92:93]
	v_pk_add_f32 v[94:95], v[94:95], v[96:97]
	v_pk_add_f32 v[82:83], v[82:83], v[86:87]
	v_pk_add_f32 v[90:91], v[90:91], v[94:95]
	s_nop 0
	v_pk_add_f32 v[82:83], v[82:83], v[90:91]
	s_nop 0
	global_store_dwordx2 v12, v[82:83], s[58:59] nt
	s_add_i32 s18, s18, 1
	s_add_i32 s20, s18, 1
	s_min_i32 s20, s20, 0x7f
	s_lshr_b32 s21, s20, 4
	s_and_b32 s22, s20, 15
	s_add_i32 s23, s18, 2
	s_min_i32 s23, s23, 0x7f
	s_and_b32 s24, s23, 15
	s_and_b32 s26, s18, 15
	s_lshr_b32 s27, s18, 4
	s_lshl_b32 s22, s22, 11
	s_lshl_b32 s24, s24, 11
	s_lshl_b32 s28, s21, 7
	s_lshl_b32 s26, s26, 11
	s_lshl_b32 s27, s27, 9
	v_add_u32_e32 v6, s22, v64
	v_add_u32_e32 v7, s24, v64
	v_add_u32_e32 v8, s28, v2
	v_lshl_add_u32 v10, v6, 9, v148
	v_lshl_add_u32 v9, v7, 9, v148
	v_add_u32_e32 v12, s26, v64
	v_lshl_add_u32 v12, v12, 12, v5
	v_add_u32_e32 v12, s27, v12
	s_waitcnt vmcnt(17)
	ds_write_b64 v149, v[152:153]
	ds_write_b64 v149, v[154:155] offset:512
	ds_read_b128 v[100:103], v150 offset:0
	ds_read_b128 v[104:107], v150 offset:16
	ds_read_b128 v[108:111], v150 offset:32
	ds_read_b128 v[112:115], v150 offset:48
	ds_read_b128 v[132:135], v150 offset:512
	ds_read_b128 v[136:139], v150 offset:528
	ds_read_b128 v[140:143], v150 offset:544
	ds_read_b128 v[144:147], v150 offset:560
	global_load_dwordx2 v[152:153], v9, s[2:3]
	global_load_dwordx2 v[154:155], v10, s[8:9]
	s_waitcnt lgkmcnt(0)
	s_waitcnt vmcnt(17)
	v_cvt_pk_f32_fp8_e32 v[44:45], v180
	v_cvt_pk_f32_fp8_sdwa v[46:47], v180 src0_sel:WORD_1
	v_cvt_pk_f32_fp8_e32 v[48:49], v181
	v_cvt_pk_f32_fp8_sdwa v[50:51], v181 src0_sel:WORD_1
	v_cvt_pk_f32_fp8_e32 v[52:53], v182
	v_cvt_pk_f32_fp8_sdwa v[54:55], v182 src0_sel:WORD_1
	v_cvt_pk_f32_fp8_e32 v[56:57], v183
	v_cvt_pk_f32_fp8_sdwa v[58:59], v183 src0_sel:WORD_1
	v_cvt_pk_f32_fp8_e32 v[66:67], v184
	v_cvt_pk_f32_fp8_sdwa v[68:69], v184 src0_sel:WORD_1
	v_cvt_pk_f32_fp8_e32 v[70:71], v185
	v_cvt_pk_f32_fp8_sdwa v[72:73], v185 src0_sel:WORD_1
	v_cvt_pk_f32_fp8_e32 v[74:75], v186
	v_cvt_pk_f32_fp8_sdwa v[76:77], v186 src0_sel:WORD_1
	v_cvt_pk_f32_fp8_e32 v[78:79], v187
	v_cvt_pk_f32_fp8_sdwa v[80:81], v187 src0_sel:WORD_1
	v_lshl_add_u32 v11, v100, 10, v8
	v_lshl_add_u32 v65, v101, 10, v8
	global_load_dwordx4 v[180:183], v11, s[6:7]
	global_load_dwordx4 v[184:187], v65, s[6:7]
	v_pk_mul_f32 v[20:21], v[44:45], v[132:133] op_sel_hi:[1,0]
	v_pk_mul_f32 v[22:23], v[46:47], v[132:133] op_sel_hi:[1,0]
	v_pk_mul_f32 v[24:25], v[48:49], v[132:133] op_sel_hi:[1,0]
	v_pk_mul_f32 v[26:27], v[50:51], v[132:133] op_sel_hi:[1,0]
	v_pk_mul_f32 v[28:29], v[52:53], v[132:133] op_sel_hi:[1,0]
	v_pk_mul_f32 v[30:31], v[54:55], v[132:133] op_sel_hi:[1,0]
	v_pk_mul_f32 v[32:33], v[56:57], v[132:133] op_sel_hi:[1,0]
	v_pk_mul_f32 v[34:35], v[58:59], v[132:133] op_sel_hi:[1,0]
	v_pk_fma_f32 v[20:21], v[66:67], v[132:133], v[20:21] op_sel:[0,1,0]
	v_pk_fma_f32 v[22:23], v[68:69], v[132:133], v[22:23] op_sel:[0,1,0]
	v_pk_fma_f32 v[24:25], v[70:71], v[132:133], v[24:25] op_sel:[0,1,0]
	v_pk_fma_f32 v[26:27], v[72:73], v[132:133], v[26:27] op_sel:[0,1,0]
	v_pk_fma_f32 v[28:29], v[74:75], v[132:133], v[28:29] op_sel:[0,1,0]
	v_pk_fma_f32 v[30:31], v[76:77], v[132:133], v[30:31] op_sel:[0,1,0]
	v_pk_fma_f32 v[32:33], v[78:79], v[132:133], v[32:33] op_sel:[0,1,0]
	v_pk_fma_f32 v[34:35], v[80:81], v[132:133], v[34:35] op_sel:[0,1,0]
	s_waitcnt vmcnt(17)
; DI void phase_peer_ffn(const Params& p) {
;     ...
; #pragma unroll
;       for (int k = 0; k < 16; ++k) {
;         const float ck = __int_as_float(__builtin_amdgcn_readlane(__float_as_int(cv), lbase + k));
; #pragma unroll
;         for (int w = 0; w < 4; ++w) {
;           f2_t lo = __builtin_amdgcn_cvt_pk_f32_fp8((int)ur[k][w], false);
;           f2_t hi = __builtin_amdgcn_cvt_pk_f32_fp8((int)ur[k][w], true);
;           yacc[4 * w] = fmaf(ck, lo[0], yacc[4 * w]);
;           yacc[4 * w + 1] = fmaf(ck, lo[1], yacc[4 * w + 1]);
;           yacc[4 * w + 2] = fmaf(ck, hi[0], yacc[4 * w + 2]);
;           yacc[4 * w + 3] = fmaf(ck, hi[1], yacc[4 * w + 3]);
;         }
	v_cvt_pk_f32_fp8_e32 v[44:45], v188
	v_cvt_pk_f32_fp8_sdwa v[46:47], v188 src0_sel:WORD_1
	v_cvt_pk_f32_fp8_e32 v[48:49], v189
	v_cvt_pk_f32_fp8_sdwa v[50:51], v189 src0_sel:WORD_1
	v_cvt_pk_f32_fp8_e32 v[52:53], v190
	v_cvt_pk_f32_fp8_sdwa v[54:55], v190 src0_sel:WORD_1
	v_cvt_pk_f32_fp8_e32 v[56:57], v191
	v_cvt_pk_f32_fp8_sdwa v[58:59], v191 src0_sel:WORD_1
	v_cvt_pk_f32_fp8_e32 v[66:67], v192
	v_cvt_pk_f32_fp8_sdwa v[68:69], v192 src0_sel:WORD_1
	v_cvt_pk_f32_fp8_e32 v[70:71], v193
	v_cvt_pk_f32_fp8_sdwa v[72:73], v193 src0_sel:WORD_1
	v_cvt_pk_f32_fp8_e32 v[74:75], v194
	v_cvt_pk_f32_fp8_sdwa v[76:77], v194 src0_sel:WORD_1
	v_cvt_pk_f32_fp8_e32 v[78:79], v195
	v_cvt_pk_f32_fp8_sdwa v[80:81], v195 src0_sel:WORD_1
	v_lshl_add_u32 v11, v102, 10, v8
	v_lshl_add_u32 v65, v103, 10, v8
	global_load_dwordx4 v[188:191], v11, s[6:7]
	global_load_dwordx4 v[192:195], v65, s[6:7]
	v_pk_fma_f32 v[20:21], v[44:45], v[134:135], v[20:21] op_sel_hi:[1,0,1]
	v_pk_fma_f32 v[22:23], v[46:47], v[134:135], v[22:23] op_sel_hi:[1,0,1]
	v_pk_fma_f32 v[24:25], v[48:49], v[134:135], v[24:25] op_sel_hi:[1,0,1]
	v_pk_fma_f32 v[26:27], v[50:51], v[134:135], v[26:27] op_sel_hi:[1,0,1]
	v_pk_fma_f32 v[28:29], v[52:53], v[134:135], v[28:29] op_sel_hi:[1,0,1]
	v_pk_fma_f32 v[30:31], v[54:55], v[134:135], v[30:31] op_sel_hi:[1,0,1]
	v_pk_fma_f32 v[32:33], v[56:57], v[134:135], v[32:33] op_sel_hi:[1,0,1]
	v_pk_fma_f32 v[34:35], v[58:59], v[134:135], v[34:35] op_sel_hi:[1,0,1]
	v_pk_fma_f32 v[20:21], v[66:67], v[134:135], v[20:21] op_sel:[0,1,0]
	v_pk_fma_f32 v[22:23], v[68:69], v[134:135], v[22:23] op_sel:[0,1,0]
	v_pk_fma_f32 v[24:25], v[70:71], v[134:135], v[24:25] op_sel:[0,1,0]
	v_pk_fma_f32 v[26:27], v[72:73], v[134:135], v[26:27] op_sel:[0,1,0]
	v_pk_fma_f32 v[28:29], v[74:75], v[134:135], v[28:29] op_sel:[0,1,0]
	v_pk_fma_f32 v[30:31], v[76:77], v[134:135], v[30:31] op_sel:[0,1,0]
	v_pk_fma_f32 v[32:33], v[78:79], v[134:135], v[32:33] op_sel:[0,1,0]
	v_pk_fma_f32 v[34:35], v[80:81], v[134:135], v[34:35] op_sel:[0,1,0]
	s_waitcnt vmcnt(17)
	v_cvt_pk_f32_fp8_e32 v[44:45], v196
	v_cvt_pk_f32_fp8_sdwa v[46:47], v196 src0_sel:WORD_1
	v_cvt_pk_f32_fp8_e32 v[48:49], v197
	v_cvt_pk_f32_fp8_sdwa v[50:51], v197 src0_sel:WORD_1
	v_cvt_pk_f32_fp8_e32 v[52:53], v198
	v_cvt_pk_f32_fp8_sdwa v[54:55], v198 src0_sel:WORD_1
	v_cvt_pk_f32_fp8_e32 v[56:57], v199
	v_cvt_pk_f32_fp8_sdwa v[58:59], v199 src0_sel:WORD_1
	v_cvt_pk_f32_fp8_e32 v[66:67], v200
	v_cvt_pk_f32_fp8_sdwa v[68:69], v200 src0_sel:WORD_1
	v_cvt_pk_f32_fp8_e32 v[70:71], v201
	v_cvt_pk_f32_fp8_sdwa v[72:73], v201 src0_sel:WORD_1
	v_cvt_pk_f32_fp8_e32 v[74:75], v202
	v_cvt_pk_f32_fp8_sdwa v[76:77], v202 src0_sel:WORD_1
	v_cvt_pk_f32_fp8_e32 v[78:79], v203
	v_cvt_pk_f32_fp8_sdwa v[80:81], v203 src0_sel:WORD_1
	v_lshl_add_u32 v11, v104, 10, v8
	v_lshl_add_u32 v65, v105, 10, v8
	global_load_dwordx4 v[196:199], v11, s[6:7]
	global_load_dwordx4 v[200:203], v65, s[6:7]
	v_pk_fma_f32 v[20:21], v[44:45], v[136:137], v[20:21] op_sel_hi:[1,0,1]
	v_pk_fma_f32 v[22:23], v[46:47], v[136:137], v[22:23] op_sel_hi:[1,0,1]
	v_pk_fma_f32 v[24:25], v[48:49], v[136:137], v[24:25] op_sel_hi:[1,0,1]
	v_pk_fma_f32 v[26:27], v[50:51], v[136:137], v[26:27] op_sel_hi:[1,0,1]
	v_pk_fma_f32 v[28:29], v[52:53], v[136:137], v[28:29] op_sel_hi:[1,0,1]
	v_pk_fma_f32 v[30:31], v[54:55], v[136:137], v[30:31] op_sel_hi:[1,0,1]
	v_pk_fma_f32 v[32:33], v[56:57], v[136:137], v[32:33] op_sel_hi:[1,0,1]
	v_pk_fma_f32 v[34:35], v[58:59], v[136:137], v[34:35] op_sel_hi:[1,0,1]
	v_pk_fma_f32 v[20:21], v[66:67], v[136:137], v[20:21] op_sel:[0,1,0]
	v_pk_fma_f32 v[22:23], v[68:69], v[136:137], v[22:23] op_sel:[0,1,0]
	v_pk_fma_f32 v[24:25], v[70:71], v[136:137], v[24:25] op_sel:[0,1,0]
	v_pk_fma_f32 v[26:27], v[72:73], v[136:137], v[26:27] op_sel:[0,1,0]
	v_pk_fma_f32 v[28:29], v[74:75], v[136:137], v[28:29] op_sel:[0,1,0]
	v_pk_fma_f32 v[30:31], v[76:77], v[136:137], v[30:31] op_sel:[0,1,0]
	v_pk_fma_f32 v[32:33], v[78:79], v[136:137], v[32:33] op_sel:[0,1,0]
	v_pk_fma_f32 v[34:35], v[80:81], v[136:137], v[34:35] op_sel:[0,1,0]
	s_waitcnt vmcnt(17)
	v_cvt_pk_f32_fp8_e32 v[44:45], v204
	v_cvt_pk_f32_fp8_sdwa v[46:47], v204 src0_sel:WORD_1
	v_cvt_pk_f32_fp8_e32 v[48:49], v205
	v_cvt_pk_f32_fp8_sdwa v[50:51], v205 src0_sel:WORD_1
	v_cvt_pk_f32_fp8_e32 v[52:53], v206
	v_cvt_pk_f32_fp8_sdwa v[54:55], v206 src0_sel:WORD_1
	v_cvt_pk_f32_fp8_e32 v[56:57], v207
	v_cvt_pk_f32_fp8_sdwa v[58:59], v207 src0_sel:WORD_1
	v_cvt_pk_f32_fp8_e32 v[66:67], v208
	v_cvt_pk_f32_fp8_sdwa v[68:69], v208 src0_sel:WORD_1
	v_cvt_pk_f32_fp8_e32 v[70:71], v209
	v_cvt_pk_f32_fp8_sdwa v[72:73], v209 src0_sel:WORD_1
	v_cvt_pk_f32_fp8_e32 v[74:75], v210
	v_cvt_pk_f32_fp8_sdwa v[76:77], v210 src0_sel:WORD_1
	v_cvt_pk_f32_fp8_e32 v[78:79], v211
	v_cvt_pk_f32_fp8_sdwa v[80:81], v211 src0_sel:WORD_1
	v_lshl_add_u32 v11, v106, 10, v8
	v_lshl_add_u32 v65, v107, 10, v8
	global_load_dwordx4 v[204:207], v11, s[6:7]
	global_load_dwordx4 v[208:211], v65, s[6:7]
	v_pk_fma_f32 v[20:21], v[44:45], v[138:139], v[20:21] op_sel_hi:[1,0,1]
	v_pk_fma_f32 v[22:23], v[46:47], v[138:139], v[22:23] op_sel_hi:[1,0,1]
	v_pk_fma_f32 v[24:25], v[48:49], v[138:139], v[24:25] op_sel_hi:[1,0,1]
	v_pk_fma_f32 v[26:27], v[50:51], v[138:139], v[26:27] op_sel_hi:[1,0,1]
	v_pk_fma_f32 v[28:29], v[52:53], v[138:139], v[28:29] op_sel_hi:[1,0,1]
	v_pk_fma_f32 v[30:31], v[54:55], v[138:139], v[30:31] op_sel_hi:[1,0,1]
	v_pk_fma_f32 v[32:33], v[56:57], v[138:139], v[32:33] op_sel_hi:[1,0,1]
	v_pk_fma_f32 v[34:35], v[58:59], v[138:139], v[34:35] op_sel_hi:[1,0,1]
	v_pk_fma_f32 v[20:21], v[66:67], v[138:139], v[20:21] op_sel:[0,1,0]
	v_pk_fma_f32 v[22:23], v[68:69], v[138:139], v[22:23] op_sel:[0,1,0]
	v_pk_fma_f32 v[24:25], v[70:71], v[138:139], v[24:25] op_sel:[0,1,0]
	v_pk_fma_f32 v[26:27], v[72:73], v[138:139], v[26:27] op_sel:[0,1,0]
	v_pk_fma_f32 v[28:29], v[74:75], v[138:139], v[28:29] op_sel:[0,1,0]
	v_pk_fma_f32 v[30:31], v[76:77], v[138:139], v[30:31] op_sel:[0,1,0]
	v_pk_fma_f32 v[32:33], v[78:79], v[138:139], v[32:33] op_sel:[0,1,0]
	v_pk_fma_f32 v[34:35], v[80:81], v[138:139], v[34:35] op_sel:[0,1,0]
	s_waitcnt vmcnt(17)
; DI void phase_peer_ffn(const Params& p) {
;     ...
; #pragma unroll
;       for (int k = 0; k < 16; ++k) {
;         const float ck = __int_as_float(__builtin_amdgcn_readlane(__float_as_int(cv), lbase + k));
; #pragma unroll
;         for (int w = 0; w < 4; ++w) {
;           f2_t lo = __builtin_amdgcn_cvt_pk_f32_fp8((int)ur[k][w], false);
;           f2_t hi = __builtin_amdgcn_cvt_pk_f32_fp8((int)ur[k][w], true);
;           yacc[4 * w] = fmaf(ck, lo[0], yacc[4 * w]);
;           yacc[4 * w + 1] = fmaf(ck, lo[1], yacc[4 * w + 1]);
;           yacc[4 * w + 2] = fmaf(ck, hi[0], yacc[4 * w + 2]);
;           yacc[4 * w + 3] = fmaf(ck, hi[1], yacc[4 * w + 3]);
;         }
	v_cvt_pk_f32_fp8_e32 v[44:45], v212
	v_cvt_pk_f32_fp8_sdwa v[46:47], v212 src0_sel:WORD_1
	v_cvt_pk_f32_fp8_e32 v[48:49], v213
	v_cvt_pk_f32_fp8_sdwa v[50:51], v213 src0_sel:WORD_1
	v_cvt_pk_f32_fp8_e32 v[52:53], v214
	v_cvt_pk_f32_fp8_sdwa v[54:55], v214 src0_sel:WORD_1
	v_cvt_pk_f32_fp8_e32 v[56:57], v215
	v_cvt_pk_f32_fp8_sdwa v[58:59], v215 src0_sel:WORD_1
	v_cvt_pk_f32_fp8_e32 v[66:67], v216
	v_cvt_pk_f32_fp8_sdwa v[68:69], v216 src0_sel:WORD_1
	v_cvt_pk_f32_fp8_e32 v[70:71], v217
	v_cvt_pk_f32_fp8_sdwa v[72:73], v217 src0_sel:WORD_1
	v_cvt_pk_f32_fp8_e32 v[74:75], v218
	v_cvt_pk_f32_fp8_sdwa v[76:77], v218 src0_sel:WORD_1
	v_cvt_pk_f32_fp8_e32 v[78:79], v219
	v_cvt_pk_f32_fp8_sdwa v[80:81], v219 src0_sel:WORD_1
	v_lshl_add_u32 v11, v108, 10, v8
	v_lshl_add_u32 v65, v109, 10, v8
	global_load_dwordx4 v[212:215], v11, s[6:7]
	global_load_dwordx4 v[216:219], v65, s[6:7]
	v_pk_fma_f32 v[20:21], v[44:45], v[140:141], v[20:21] op_sel_hi:[1,0,1]
	v_pk_fma_f32 v[22:23], v[46:47], v[140:141], v[22:23] op_sel_hi:[1,0,1]
	v_pk_fma_f32 v[24:25], v[48:49], v[140:141], v[24:25] op_sel_hi:[1,0,1]
	v_pk_fma_f32 v[26:27], v[50:51], v[140:141], v[26:27] op_sel_hi:[1,0,1]
	v_pk_fma_f32 v[28:29], v[52:53], v[140:141], v[28:29] op_sel_hi:[1,0,1]
	v_pk_fma_f32 v[30:31], v[54:55], v[140:141], v[30:31] op_sel_hi:[1,0,1]
	v_pk_fma_f32 v[32:33], v[56:57], v[140:141], v[32:33] op_sel_hi:[1,0,1]
	v_pk_fma_f32 v[34:35], v[58:59], v[140:141], v[34:35] op_sel_hi:[1,0,1]
	v_pk_fma_f32 v[20:21], v[66:67], v[140:141], v[20:21] op_sel:[0,1,0]
	v_pk_fma_f32 v[22:23], v[68:69], v[140:141], v[22:23] op_sel:[0,1,0]
	v_pk_fma_f32 v[24:25], v[70:71], v[140:141], v[24:25] op_sel:[0,1,0]
	v_pk_fma_f32 v[26:27], v[72:73], v[140:141], v[26:27] op_sel:[0,1,0]
	v_pk_fma_f32 v[28:29], v[74:75], v[140:141], v[28:29] op_sel:[0,1,0]
	v_pk_fma_f32 v[30:31], v[76:77], v[140:141], v[30:31] op_sel:[0,1,0]
	v_pk_fma_f32 v[32:33], v[78:79], v[140:141], v[32:33] op_sel:[0,1,0]
	v_pk_fma_f32 v[34:35], v[80:81], v[140:141], v[34:35] op_sel:[0,1,0]
	s_waitcnt vmcnt(17)
	v_cvt_pk_f32_fp8_e32 v[44:45], v220
	v_cvt_pk_f32_fp8_sdwa v[46:47], v220 src0_sel:WORD_1
	v_cvt_pk_f32_fp8_e32 v[48:49], v221
	v_cvt_pk_f32_fp8_sdwa v[50:51], v221 src0_sel:WORD_1
	v_cvt_pk_f32_fp8_e32 v[52:53], v222
	v_cvt_pk_f32_fp8_sdwa v[54:55], v222 src0_sel:WORD_1
	v_cvt_pk_f32_fp8_e32 v[56:57], v223
	v_cvt_pk_f32_fp8_sdwa v[58:59], v223 src0_sel:WORD_1
	v_cvt_pk_f32_fp8_e32 v[66:67], v224
	v_cvt_pk_f32_fp8_sdwa v[68:69], v224 src0_sel:WORD_1
	v_cvt_pk_f32_fp8_e32 v[70:71], v225
	v_cvt_pk_f32_fp8_sdwa v[72:73], v225 src0_sel:WORD_1
	v_cvt_pk_f32_fp8_e32 v[74:75], v226
	v_cvt_pk_f32_fp8_sdwa v[76:77], v226 src0_sel:WORD_1
	v_cvt_pk_f32_fp8_e32 v[78:79], v227
	v_cvt_pk_f32_fp8_sdwa v[80:81], v227 src0_sel:WORD_1
	v_lshl_add_u32 v11, v110, 10, v8
	v_lshl_add_u32 v65, v111, 10, v8
	global_load_dwordx4 v[220:223], v11, s[6:7]
	global_load_dwordx4 v[224:227], v65, s[6:7]
	v_pk_fma_f32 v[20:21], v[44:45], v[142:143], v[20:21] op_sel_hi:[1,0,1]
	v_pk_fma_f32 v[22:23], v[46:47], v[142:143], v[22:23] op_sel_hi:[1,0,1]
	v_pk_fma_f32 v[24:25], v[48:49], v[142:143], v[24:25] op_sel_hi:[1,0,1]
	v_pk_fma_f32 v[26:27], v[50:51], v[142:143], v[26:27] op_sel_hi:[1,0,1]
	v_pk_fma_f32 v[28:29], v[52:53], v[142:143], v[28:29] op_sel_hi:[1,0,1]
	v_pk_fma_f32 v[30:31], v[54:55], v[142:143], v[30:31] op_sel_hi:[1,0,1]
	v_pk_fma_f32 v[32:33], v[56:57], v[142:143], v[32:33] op_sel_hi:[1,0,1]
	v_pk_fma_f32 v[34:35], v[58:59], v[142:143], v[34:35] op_sel_hi:[1,0,1]
	v_pk_fma_f32 v[20:21], v[66:67], v[142:143], v[20:21] op_sel:[0,1,0]
	v_pk_fma_f32 v[22:23], v[68:69], v[142:143], v[22:23] op_sel:[0,1,0]
	v_pk_fma_f32 v[24:25], v[70:71], v[142:143], v[24:25] op_sel:[0,1,0]
	v_pk_fma_f32 v[26:27], v[72:73], v[142:143], v[26:27] op_sel:[0,1,0]
	v_pk_fma_f32 v[28:29], v[74:75], v[142:143], v[28:29] op_sel:[0,1,0]
	v_pk_fma_f32 v[30:31], v[76:77], v[142:143], v[30:31] op_sel:[0,1,0]
	v_pk_fma_f32 v[32:33], v[78:79], v[142:143], v[32:33] op_sel:[0,1,0]
	v_pk_fma_f32 v[34:35], v[80:81], v[142:143], v[34:35] op_sel:[0,1,0]
	s_waitcnt vmcnt(17)
; DI void phase_peer_ffn(const Params& p) {
;     ...
; #pragma unroll
;       for (int k = 0; k < 16; ++k) {
;         const float ck = __int_as_float(__builtin_amdgcn_readlane(__float_as_int(cv), lbase + k));
; #pragma unroll
;         for (int w = 0; w < 4; ++w) {
;           f2_t lo = __builtin_amdgcn_cvt_pk_f32_fp8((int)ur[k][w], false);
;           f2_t hi = __builtin_amdgcn_cvt_pk_f32_fp8((int)ur[k][w], true);
;           yacc[4 * w] = fmaf(ck, lo[0], yacc[4 * w]);
;           yacc[4 * w + 1] = fmaf(ck, lo[1], yacc[4 * w + 1]);
;           yacc[4 * w + 2] = fmaf(ck, hi[0], yacc[4 * w + 2]);
;           yacc[4 * w + 3] = fmaf(ck, hi[1], yacc[4 * w + 3]);
;         }
;     ...
;     const float* xr = h + (size_t)tok * 1024 + lane * 16;
;     float v[16];
; #pragma unroll
;     for (int c = 0; c < 4; ++c) {
;       f32x4 t = *reinterpret_cast<const f32x4*>(xr + c * 4);
; #pragma unroll
;       for (int k = 0; k < 4; ++k) v[4 * c + k] = ALPHA * t[k] + yacc[4 * c + k];
;     }
;     float s = 0.f;
; #pragma unroll
;     for (int i = 0; i < 16; ++i) s += v[i];
;     const float mean = wave_sum(s) * (1.f / 1024.f);
;     float q = 0.f;
; #pragma unroll
;     for (int i = 0; i < 16; ++i) { float d = v[i] - mean; q += d * d; }
;     const float rstd = rsqrtf(wave_sum(q) * (1.f / 1024.f) + 1e-5f);
;     float* orow = p.out + (size_t)tok * 1024 + lane * 16;
; #pragma unroll
;     for (int c = 0; c < 4; ++c) {
;       f32x4 gg = *reinterpret_cast<const f32x4*>(p.ln_ffn_g + lane * 16 + c * 4);
;       f32x4 bb = *reinterpret_cast<const f32x4*>(p.ln_ffn_b + lane * 16 + c * 4);
	v_cvt_pk_f32_fp8_e32 v[44:45], v228
	v_cvt_pk_f32_fp8_sdwa v[46:47], v228 src0_sel:WORD_1
	v_cvt_pk_f32_fp8_e32 v[48:49], v229
	v_cvt_pk_f32_fp8_sdwa v[50:51], v229 src0_sel:WORD_1
	v_cvt_pk_f32_fp8_e32 v[52:53], v230
	v_cvt_pk_f32_fp8_sdwa v[54:55], v230 src0_sel:WORD_1
	v_cvt_pk_f32_fp8_e32 v[56:57], v231
	v_cvt_pk_f32_fp8_sdwa v[58:59], v231 src0_sel:WORD_1
	v_cvt_pk_f32_fp8_e32 v[66:67], v232
	v_cvt_pk_f32_fp8_sdwa v[68:69], v232 src0_sel:WORD_1
	v_cvt_pk_f32_fp8_e32 v[70:71], v233
	v_cvt_pk_f32_fp8_sdwa v[72:73], v233 src0_sel:WORD_1
	v_cvt_pk_f32_fp8_e32 v[74:75], v234
	v_cvt_pk_f32_fp8_sdwa v[76:77], v234 src0_sel:WORD_1
	v_cvt_pk_f32_fp8_e32 v[78:79], v235
	v_cvt_pk_f32_fp8_sdwa v[80:81], v235 src0_sel:WORD_1
	v_lshl_add_u32 v11, v112, 10, v8
	v_lshl_add_u32 v65, v113, 10, v8
	global_load_dwordx4 v[228:231], v11, s[6:7]
	global_load_dwordx4 v[232:235], v65, s[6:7]
	v_pk_fma_f32 v[20:21], v[44:45], v[144:145], v[20:21] op_sel_hi:[1,0,1]
	v_pk_fma_f32 v[22:23], v[46:47], v[144:145], v[22:23] op_sel_hi:[1,0,1]
	v_pk_fma_f32 v[24:25], v[48:49], v[144:145], v[24:25] op_sel_hi:[1,0,1]
	v_pk_fma_f32 v[26:27], v[50:51], v[144:145], v[26:27] op_sel_hi:[1,0,1]
	v_pk_fma_f32 v[28:29], v[52:53], v[144:145], v[28:29] op_sel_hi:[1,0,1]
	v_pk_fma_f32 v[30:31], v[54:55], v[144:145], v[30:31] op_sel_hi:[1,0,1]
	v_pk_fma_f32 v[32:33], v[56:57], v[144:145], v[32:33] op_sel_hi:[1,0,1]
	v_pk_fma_f32 v[34:35], v[58:59], v[144:145], v[34:35] op_sel_hi:[1,0,1]
	v_pk_fma_f32 v[20:21], v[66:67], v[144:145], v[20:21] op_sel:[0,1,0]
	v_pk_fma_f32 v[22:23], v[68:69], v[144:145], v[22:23] op_sel:[0,1,0]
	v_pk_fma_f32 v[24:25], v[70:71], v[144:145], v[24:25] op_sel:[0,1,0]
	v_pk_fma_f32 v[26:27], v[72:73], v[144:145], v[26:27] op_sel:[0,1,0]
	v_pk_fma_f32 v[28:29], v[74:75], v[144:145], v[28:29] op_sel:[0,1,0]
	v_pk_fma_f32 v[30:31], v[76:77], v[144:145], v[30:31] op_sel:[0,1,0]
	v_pk_fma_f32 v[32:33], v[78:79], v[144:145], v[32:33] op_sel:[0,1,0]
	v_pk_fma_f32 v[34:35], v[80:81], v[144:145], v[34:35] op_sel:[0,1,0]
	s_waitcnt vmcnt(17)
	v_cvt_pk_f32_fp8_e32 v[44:45], v236
	v_cvt_pk_f32_fp8_sdwa v[46:47], v236 src0_sel:WORD_1
	v_cvt_pk_f32_fp8_e32 v[48:49], v237
	v_cvt_pk_f32_fp8_sdwa v[50:51], v237 src0_sel:WORD_1
	v_cvt_pk_f32_fp8_e32 v[52:53], v238
	v_cvt_pk_f32_fp8_sdwa v[54:55], v238 src0_sel:WORD_1
	v_cvt_pk_f32_fp8_e32 v[56:57], v239
	v_cvt_pk_f32_fp8_sdwa v[58:59], v239 src0_sel:WORD_1
	v_cvt_pk_f32_fp8_e32 v[66:67], v240
	v_cvt_pk_f32_fp8_sdwa v[68:69], v240 src0_sel:WORD_1
	v_cvt_pk_f32_fp8_e32 v[70:71], v241
	v_cvt_pk_f32_fp8_sdwa v[72:73], v241 src0_sel:WORD_1
	v_cvt_pk_f32_fp8_e32 v[74:75], v242
	v_cvt_pk_f32_fp8_sdwa v[76:77], v242 src0_sel:WORD_1
	v_cvt_pk_f32_fp8_e32 v[78:79], v243
	v_cvt_pk_f32_fp8_sdwa v[80:81], v243 src0_sel:WORD_1
	v_lshl_add_u32 v11, v114, 10, v8
	v_lshl_add_u32 v65, v115, 10, v8
	global_load_dwordx4 v[236:239], v11, s[6:7]
	global_load_dwordx4 v[240:243], v65, s[6:7]
	v_pk_fma_f32 v[20:21], v[44:45], v[146:147], v[20:21] op_sel_hi:[1,0,1]
	v_pk_fma_f32 v[22:23], v[46:47], v[146:147], v[22:23] op_sel_hi:[1,0,1]
	v_pk_fma_f32 v[24:25], v[48:49], v[146:147], v[24:25] op_sel_hi:[1,0,1]
	v_pk_fma_f32 v[26:27], v[50:51], v[146:147], v[26:27] op_sel_hi:[1,0,1]
	v_pk_fma_f32 v[28:29], v[52:53], v[146:147], v[28:29] op_sel_hi:[1,0,1]
	v_pk_fma_f32 v[30:31], v[54:55], v[146:147], v[30:31] op_sel_hi:[1,0,1]
	v_pk_fma_f32 v[32:33], v[56:57], v[146:147], v[32:33] op_sel_hi:[1,0,1]
	v_pk_fma_f32 v[34:35], v[58:59], v[146:147], v[34:35] op_sel_hi:[1,0,1]
	v_pk_fma_f32 v[20:21], v[66:67], v[146:147], v[20:21] op_sel:[0,1,0]
	v_pk_fma_f32 v[22:23], v[68:69], v[146:147], v[22:23] op_sel:[0,1,0]
	v_pk_fma_f32 v[24:25], v[70:71], v[146:147], v[24:25] op_sel:[0,1,0]
	v_pk_fma_f32 v[26:27], v[72:73], v[146:147], v[26:27] op_sel:[0,1,0]
	v_pk_fma_f32 v[28:29], v[74:75], v[146:147], v[28:29] op_sel:[0,1,0]
	v_pk_fma_f32 v[30:31], v[76:77], v[146:147], v[30:31] op_sel:[0,1,0]
	v_pk_fma_f32 v[32:33], v[78:79], v[146:147], v[32:33] op_sel:[0,1,0]
	v_pk_fma_f32 v[34:35], v[80:81], v[146:147], v[34:35] op_sel:[0,1,0]
	ds_write_b128 v3, v[20:23] offset:0
	ds_write_b128 v3, v[24:27] offset:128
	ds_write_b128 v3, v[28:31] offset:256
	ds_write_b128 v3, v[32:35] offset:384
	ds_read_b64 v[82:83], v4 offset:0
	ds_read_b64 v[84:85], v4 offset:512
	ds_read_b64 v[86:87], v4 offset:1024
	ds_read_b64 v[88:89], v4 offset:1536
	ds_read_b64 v[90:91], v4 offset:2048
	ds_read_b64 v[92:93], v4 offset:2560
	ds_read_b64 v[94:95], v4 offset:3072
	ds_read_b64 v[96:97], v4 offset:3584
	s_waitcnt lgkmcnt(0)
	v_pk_add_f32 v[82:83], v[82:83], v[84:85]
	v_pk_add_f32 v[86:87], v[86:87], v[88:89]
	v_pk_add_f32 v[90:91], v[90:91], v[92:93]
	v_pk_add_f32 v[94:95], v[94:95], v[96:97]
	v_pk_add_f32 v[82:83], v[82:83], v[86:87]
	v_pk_add_f32 v[90:91], v[90:91], v[94:95]
	s_nop 0
	v_pk_add_f32 v[82:83], v[82:83], v[90:91]
	s_nop 0
	global_store_dwordx2 v12, v[82:83], s[58:59] nt
	s_add_i32 s18, s18, 1
	s_cmpk_lt_u32 s18, 0x80
	s_cbranch_scc1 .Lpf_loop
	s_waitcnt vmcnt(0) lgkmcnt(0)
	v_lshlrev_b32_e32 v1, 6, v0
	global_load_dwordx4 v[100:103], v1, s[54:55]
	global_load_dwordx4 v[104:107], v1, s[54:55] offset:16
	global_load_dwordx4 v[108:111], v1, s[54:55] offset:32
	global_load_dwordx4 v[112:115], v1, s[54:55] offset:48
	global_load_dwordx4 v[116:119], v1, s[56:57]
	global_load_dwordx4 v[120:123], v1, s[56:57] offset:16
	global_load_dwordx4 v[124:127], v1, s[56:57] offset:32
	global_load_dwordx4 v[128:131], v1, s[56:57] offset:48
	s_mov_b32 s4, 0x3f9837f0
	s_mov_b32 s5, 0
	v_mov_b32_e32 v3, 0x3727c5ac
	s_mov_b32 s18, 0
	s_mov_b32 s19, 0x800
	v_add_u32_e32 v2, s18, v64
	v_lshl_add_u32 v2, v2, 12, v1
	global_load_dwordx4 v[20:23], v2, s[58:59] sc1
	global_load_dwordx4 v[24:27], v2, s[58:59] offset:16 sc1
	global_load_dwordx4 v[28:31], v2, s[58:59] offset:32 sc1
	global_load_dwordx4 v[32:35], v2, s[58:59] offset:48 sc1
	global_load_dwordx4 v[36:39], v2, s[82:83]
	global_load_dwordx4 v[40:43], v2, s[82:83] offset:16
	global_load_dwordx4 v[44:47], v2, s[82:83] offset:32
	global_load_dwordx4 v[48:51], v2, s[82:83] offset:48
